# GEMM trip-loop heads aligned to 64 bytes (p2align 6), otherwise the gk0+mixers+group-barrier-shortcut version
# baseline (speedup 1.0000x reference)
.LBB0_118:
	s_ashr_i32 s41, s40, 31
	s_lshl_b64 s[8:9], s[40:41], 19
	s_add_u32 s42, s60, s8
	s_addc_u32 s43, s61, s9
	s_and_b64 s[8:9], s[36:37], exec
	s_cselect_b32 s12, s43, s7
	s_cselect_b32 s14, s42, s6
	s_ashr_i32 s39, s38, 31
	s_lshl_b64 s[8:9], s[38:39], 19
	v_readlane_b32 s15, v255, 1
	s_add_u32 s44, s15, s8
	v_readlane_b32 s8, v255, 2
	s_addc_u32 s45, s8, s9
	s_and_b64 s[8:9], s[36:37], exec
	s_cselect_b32 s15, s45, s49
	s_cselect_b32 s16, s44, s48
	s_add_u32 s46, s6, 0x40080
	s_addc_u32 s47, s7, 0
	s_add_u32 s17, s48, 0x100
	v_mov_b32_e32 v0, 0
	s_addc_u32 s23, s49, 0
	s_mov_b32 s30, -2
	v_mov_b32_e32 v1, v0
	v_mov_b32_e32 v2, v0
	v_mov_b32_e32 v3, v0
	v_mov_b32_e32 v4, v0
	v_mov_b32_e32 v5, v0
	v_mov_b32_e32 v6, v0
	v_mov_b32_e32 v7, v0
	v_mov_b32_e32 v16, v0
	v_mov_b32_e32 v17, v0
	v_mov_b32_e32 v18, v0
	v_mov_b32_e32 v19, v0
	v_mov_b32_e32 v20, v0
	v_mov_b32_e32 v21, v0
	v_mov_b32_e32 v22, v0
	v_mov_b32_e32 v23, v0
	v_mov_b32_e32 v32, v0
	v_mov_b32_e32 v33, v0
	v_mov_b32_e32 v34, v0
	v_mov_b32_e32 v35, v0
	v_mov_b32_e32 v36, v0
	v_mov_b32_e32 v37, v0
	v_mov_b32_e32 v38, v0
	v_mov_b32_e32 v39, v0
	v_mov_b32_e32 v48, v0
	v_mov_b32_e32 v49, v0
	v_mov_b32_e32 v50, v0
	v_mov_b32_e32 v51, v0
	v_mov_b32_e32 v52, v0
	v_mov_b32_e32 v53, v0
	v_mov_b32_e32 v54, v0
	v_mov_b32_e32 v55, v0
	v_mov_b32_e32 v8, v0
	v_mov_b32_e32 v9, v0
	v_mov_b32_e32 v10, v0
	v_mov_b32_e32 v11, v0
	v_mov_b32_e32 v12, v0
	v_mov_b32_e32 v13, v0
	v_mov_b32_e32 v14, v0
	v_mov_b32_e32 v15, v0
	v_mov_b32_e32 v24, v0
	v_mov_b32_e32 v25, v0
	v_mov_b32_e32 v26, v0
	v_mov_b32_e32 v27, v0
	v_mov_b32_e32 v28, v0
	v_mov_b32_e32 v29, v0
	v_mov_b32_e32 v30, v0
	v_mov_b32_e32 v31, v0
	v_mov_b32_e32 v40, v0
	v_mov_b32_e32 v41, v0
	v_mov_b32_e32 v42, v0
	v_mov_b32_e32 v43, v0
	v_mov_b32_e32 v44, v0
	v_mov_b32_e32 v45, v0
	v_mov_b32_e32 v46, v0
	v_mov_b32_e32 v47, v0
	v_mov_b32_e32 v56, v0
	v_mov_b32_e32 v57, v0
	v_mov_b32_e32 v58, v0
	v_mov_b32_e32 v59, v0
	v_mov_b32_e32 v60, v0
	v_mov_b32_e32 v61, v0
	v_mov_b32_e32 v62, v0
	v_mov_b32_e32 v63, v0
	v_mov_b32_e32 v64, v0
	v_mov_b32_e32 v65, v0
	v_mov_b32_e32 v66, v0
	v_mov_b32_e32 v67, v0
	v_mov_b32_e32 v68, v0
	v_mov_b32_e32 v69, v0
	v_mov_b32_e32 v70, v0
	v_mov_b32_e32 v71, v0
	v_mov_b32_e32 v80, v0
	v_mov_b32_e32 v81, v0
	v_mov_b32_e32 v82, v0
	v_mov_b32_e32 v83, v0
	v_mov_b32_e32 v84, v0
	v_mov_b32_e32 v85, v0
	v_mov_b32_e32 v86, v0
	v_mov_b32_e32 v87, v0
	v_mov_b32_e32 v96, v0
	v_mov_b32_e32 v97, v0
	v_mov_b32_e32 v98, v0
	v_mov_b32_e32 v99, v0
	v_mov_b32_e32 v100, v0
	v_mov_b32_e32 v101, v0
	v_mov_b32_e32 v102, v0
	v_mov_b32_e32 v103, v0
	v_mov_b32_e32 v112, v0
	v_mov_b32_e32 v113, v0
	v_mov_b32_e32 v114, v0
	v_mov_b32_e32 v115, v0
	v_mov_b32_e32 v116, v0
	v_mov_b32_e32 v117, v0
	v_mov_b32_e32 v118, v0
	v_mov_b32_e32 v119, v0
	v_mov_b32_e32 v72, v0
	v_mov_b32_e32 v73, v0
	v_mov_b32_e32 v74, v0
	v_mov_b32_e32 v75, v0
	v_mov_b32_e32 v76, v0
	v_mov_b32_e32 v77, v0
	v_mov_b32_e32 v78, v0
	v_mov_b32_e32 v79, v0
	v_mov_b32_e32 v88, v0
	v_mov_b32_e32 v89, v0
	v_mov_b32_e32 v90, v0
	v_mov_b32_e32 v91, v0
	v_mov_b32_e32 v92, v0
	v_mov_b32_e32 v93, v0
	v_mov_b32_e32 v94, v0
	v_mov_b32_e32 v95, v0
	v_mov_b32_e32 v104, v0
	v_mov_b32_e32 v105, v0
	v_mov_b32_e32 v106, v0
	v_mov_b32_e32 v107, v0
	v_mov_b32_e32 v108, v0
	v_mov_b32_e32 v109, v0
	v_mov_b32_e32 v110, v0
	v_mov_b32_e32 v111, v0
	v_mov_b32_e32 v120, v0
	v_mov_b32_e32 v121, v0
	v_mov_b32_e32 v122, v0
	v_mov_b32_e32 v123, v0
	v_mov_b32_e32 v124, v0
	v_mov_b32_e32 v125, v0
	v_mov_b32_e32 v126, v0
	v_mov_b32_e32 v127, v0
	.p2align 6

.LBB0_155:
	s_ashr_i32 s43, s42, 31
	s_lshl_b64 s[6:7], s[42:43], 19
	v_readlane_b32 s8, v251, 20
	s_add_u32 s44, s8, s6
	v_readlane_b32 s6, v251, 21
	s_addc_u32 s45, s6, s7
	s_and_b64 s[6:7], s[38:39], exec
	s_cselect_b32 s23, s45, s49
	s_cselect_b32 s24, s44, s48
	s_ashr_i32 s41, s40, 31
	s_lshl_b64 s[6:7], s[40:41], 19
	v_readlane_b32 s8, v251, 22
	s_add_u32 s46, s8, s6
	v_readlane_b32 s6, v251, 23
	s_addc_u32 s47, s6, s7
	s_and_b64 s[6:7], s[38:39], exec
	s_cselect_b32 s25, s47, s51
	s_cselect_b32 s30, s46, s50
	s_add_u32 s48, s48, 0x40080
	s_addc_u32 s49, s49, 0
	s_add_u32 s31, s50, 0x100
	v_mov_b32_e32 v0, 0
	s_addc_u32 s33, s51, 0
	s_mov_b32 s37, -2
	v_mov_b32_e32 v1, v0
	v_mov_b32_e32 v2, v0
	v_mov_b32_e32 v3, v0
	v_mov_b32_e32 v4, v0
	v_mov_b32_e32 v5, v0
	v_mov_b32_e32 v6, v0
	v_mov_b32_e32 v7, v0
	v_mov_b32_e32 v8, v0
	v_mov_b32_e32 v9, v0
	v_mov_b32_e32 v10, v0
	v_mov_b32_e32 v11, v0
	v_mov_b32_e32 v12, v0
	v_mov_b32_e32 v13, v0
	v_mov_b32_e32 v14, v0
	v_mov_b32_e32 v15, v0
	v_mov_b32_e32 v24, v0
	v_mov_b32_e32 v25, v0
	v_mov_b32_e32 v26, v0
	v_mov_b32_e32 v27, v0
	v_mov_b32_e32 v28, v0
	v_mov_b32_e32 v29, v0
	v_mov_b32_e32 v30, v0
	v_mov_b32_e32 v31, v0
	v_mov_b32_e32 v40, v0
	v_mov_b32_e32 v41, v0
	v_mov_b32_e32 v42, v0
	v_mov_b32_e32 v43, v0
	v_mov_b32_e32 v44, v0
	v_mov_b32_e32 v45, v0
	v_mov_b32_e32 v46, v0
	v_mov_b32_e32 v47, v0
	v_mov_b32_e32 v16, v0
	v_mov_b32_e32 v17, v0
	v_mov_b32_e32 v18, v0
	v_mov_b32_e32 v19, v0
	v_mov_b32_e32 v20, v0
	v_mov_b32_e32 v21, v0
	v_mov_b32_e32 v22, v0
	v_mov_b32_e32 v23, v0
	v_mov_b32_e32 v32, v0
	v_mov_b32_e32 v33, v0
	v_mov_b32_e32 v34, v0
	v_mov_b32_e32 v35, v0
	v_mov_b32_e32 v36, v0
	v_mov_b32_e32 v37, v0
	v_mov_b32_e32 v38, v0
	v_mov_b32_e32 v39, v0
	v_mov_b32_e32 v48, v0
	v_mov_b32_e32 v49, v0
	v_mov_b32_e32 v50, v0
	v_mov_b32_e32 v51, v0
	v_mov_b32_e32 v52, v0
	v_mov_b32_e32 v53, v0
	v_mov_b32_e32 v54, v0
	v_mov_b32_e32 v55, v0
	v_mov_b32_e32 v56, v0
	v_mov_b32_e32 v57, v0
	v_mov_b32_e32 v58, v0
	v_mov_b32_e32 v59, v0
	v_mov_b32_e32 v60, v0
	v_mov_b32_e32 v61, v0
	v_mov_b32_e32 v62, v0
	v_mov_b32_e32 v63, v0
	v_mov_b32_e32 v64, v0
	v_mov_b32_e32 v65, v0
	v_mov_b32_e32 v66, v0
	v_mov_b32_e32 v67, v0
	v_mov_b32_e32 v68, v0
	v_mov_b32_e32 v69, v0
	v_mov_b32_e32 v70, v0
	v_mov_b32_e32 v71, v0
	v_mov_b32_e32 v72, v0
	v_mov_b32_e32 v73, v0
	v_mov_b32_e32 v74, v0
	v_mov_b32_e32 v75, v0
	v_mov_b32_e32 v76, v0
	v_mov_b32_e32 v77, v0
	v_mov_b32_e32 v78, v0
	v_mov_b32_e32 v79, v0
	v_mov_b32_e32 v88, v0
	v_mov_b32_e32 v89, v0
	v_mov_b32_e32 v90, v0
	v_mov_b32_e32 v91, v0
	v_mov_b32_e32 v92, v0
	v_mov_b32_e32 v93, v0
	v_mov_b32_e32 v94, v0
	v_mov_b32_e32 v95, v0
	v_mov_b32_e32 v104, v0
	v_mov_b32_e32 v105, v0
	v_mov_b32_e32 v106, v0
	v_mov_b32_e32 v107, v0
	v_mov_b32_e32 v108, v0
	v_mov_b32_e32 v109, v0
	v_mov_b32_e32 v110, v0
	v_mov_b32_e32 v111, v0
	v_mov_b32_e32 v80, v0
	v_mov_b32_e32 v81, v0
	v_mov_b32_e32 v82, v0
	v_mov_b32_e32 v83, v0
	v_mov_b32_e32 v84, v0
	v_mov_b32_e32 v85, v0
	v_mov_b32_e32 v86, v0
	v_mov_b32_e32 v87, v0
	v_mov_b32_e32 v96, v0
	v_mov_b32_e32 v97, v0
	v_mov_b32_e32 v98, v0
	v_mov_b32_e32 v99, v0
	v_mov_b32_e32 v100, v0
	v_mov_b32_e32 v101, v0
	v_mov_b32_e32 v102, v0
	v_mov_b32_e32 v103, v0
	v_mov_b32_e32 v112, v0
	v_mov_b32_e32 v113, v0
	v_mov_b32_e32 v114, v0
	v_mov_b32_e32 v115, v0
	v_mov_b32_e32 v116, v0
	v_mov_b32_e32 v117, v0
	v_mov_b32_e32 v118, v0
	v_mov_b32_e32 v119, v0
	v_mov_b32_e32 v120, v0
	v_mov_b32_e32 v121, v0
	v_mov_b32_e32 v122, v0
	v_mov_b32_e32 v123, v0
	v_mov_b32_e32 v124, v0
	v_mov_b32_e32 v125, v0
	v_mov_b32_e32 v126, v0
	v_mov_b32_e32 v127, v0
	.p2align 6

.LBB0_285:
	v_lshl_add_u64 v[142:143], s[44:45], 0, v[110:111]
	v_lshl_add_u64 v[156:157], s[44:45], 0, v[128:129]
	v_lshl_add_u64 v[158:159], s[4:5], 0, v[130:131]
	v_lshl_add_u64 v[160:161], s[4:5], 0, v[140:141]
	s_mov_b32 s3, -2
	s_mov_b64 s[48:49], 0
	.p2align 6

.LBB0_408:
	s_ashr_i32 s41, s40, 31
	s_lshl_b64 s[8:9], s[40:41], 19
	s_add_u32 s42, s60, s8
	s_addc_u32 s43, s61, s9
	s_and_b64 s[8:9], s[36:37], exec
	s_cselect_b32 s12, s43, s7
	s_cselect_b32 s14, s42, s6
	s_ashr_i32 s39, s38, 31
	s_lshl_b64 s[8:9], s[38:39], 19
	s_add_u32 s44, s13, s8
	s_addc_u32 s45, s24, s9
	s_and_b64 s[8:9], s[36:37], exec
	s_cselect_b32 s15, s45, s49
	s_cselect_b32 s16, s44, s48
	s_add_u32 s46, s6, 0x40080
	s_addc_u32 s47, s7, 0
	s_add_u32 s17, s48, 0x100
	v_mov_b32_e32 v0, 0
	s_addc_u32 s23, s49, 0
	s_mov_b32 s30, -2
	v_mov_b32_e32 v1, v0
	v_mov_b32_e32 v2, v0
	v_mov_b32_e32 v3, v0
	v_mov_b32_e32 v4, v0
	v_mov_b32_e32 v5, v0
	v_mov_b32_e32 v6, v0
	v_mov_b32_e32 v7, v0
	v_mov_b32_e32 v8, v0
	v_mov_b32_e32 v9, v0
	v_mov_b32_e32 v10, v0
	v_mov_b32_e32 v11, v0
	v_mov_b32_e32 v16, v0
	v_mov_b32_e32 v17, v0
	v_mov_b32_e32 v18, v0
	v_mov_b32_e32 v19, v0
	v_mov_b32_e32 v28, v0
	v_mov_b32_e32 v29, v0
	v_mov_b32_e32 v30, v0
	v_mov_b32_e32 v31, v0
	v_mov_b32_e32 v36, v0
	v_mov_b32_e32 v37, v0
	v_mov_b32_e32 v38, v0
	v_mov_b32_e32 v39, v0
	v_mov_b32_e32 v40, v0
	v_mov_b32_e32 v41, v0
	v_mov_b32_e32 v42, v0
	v_mov_b32_e32 v43, v0
	v_mov_b32_e32 v48, v0
	v_mov_b32_e32 v49, v0
	v_mov_b32_e32 v50, v0
	v_mov_b32_e32 v51, v0
	v_mov_b32_e32 v12, v0
	v_mov_b32_e32 v13, v0
	v_mov_b32_e32 v14, v0
	v_mov_b32_e32 v15, v0
	v_mov_b32_e32 v20, v0
	v_mov_b32_e32 v21, v0
	v_mov_b32_e32 v22, v0
	v_mov_b32_e32 v23, v0
	v_mov_b32_e32 v24, v0
	v_mov_b32_e32 v25, v0
	v_mov_b32_e32 v26, v0
	v_mov_b32_e32 v27, v0
	v_mov_b32_e32 v32, v0
	v_mov_b32_e32 v33, v0
	v_mov_b32_e32 v34, v0
	v_mov_b32_e32 v35, v0
	v_mov_b32_e32 v44, v0
	v_mov_b32_e32 v45, v0
	v_mov_b32_e32 v46, v0
	v_mov_b32_e32 v47, v0
	v_mov_b32_e32 v52, v0
	v_mov_b32_e32 v53, v0
	v_mov_b32_e32 v54, v0
	v_mov_b32_e32 v55, v0
	v_mov_b32_e32 v56, v0
	v_mov_b32_e32 v57, v0
	v_mov_b32_e32 v58, v0
	v_mov_b32_e32 v59, v0
	v_mov_b32_e32 v60, v0
	v_mov_b32_e32 v61, v0
	v_mov_b32_e32 v62, v0
	v_mov_b32_e32 v63, v0
	v_mov_b32_e32 v64, v0
	v_mov_b32_e32 v65, v0
	v_mov_b32_e32 v66, v0
	v_mov_b32_e32 v67, v0
	v_mov_b32_e32 v68, v0
	v_mov_b32_e32 v69, v0
	v_mov_b32_e32 v70, v0
	v_mov_b32_e32 v71, v0
	v_mov_b32_e32 v80, v0
	v_mov_b32_e32 v81, v0
	v_mov_b32_e32 v82, v0
	v_mov_b32_e32 v83, v0
	v_mov_b32_e32 v84, v0
	v_mov_b32_e32 v85, v0
	v_mov_b32_e32 v86, v0
	v_mov_b32_e32 v87, v0
	v_mov_b32_e32 v96, v0
	v_mov_b32_e32 v97, v0
	v_mov_b32_e32 v98, v0
	v_mov_b32_e32 v99, v0
	v_mov_b32_e32 v100, v0
	v_mov_b32_e32 v101, v0
	v_mov_b32_e32 v102, v0
	v_mov_b32_e32 v103, v0
	v_mov_b32_e32 v112, v0
	v_mov_b32_e32 v113, v0
	v_mov_b32_e32 v114, v0
	v_mov_b32_e32 v115, v0
	v_mov_b32_e32 v116, v0
	v_mov_b32_e32 v117, v0
	v_mov_b32_e32 v118, v0
	v_mov_b32_e32 v119, v0
	v_mov_b32_e32 v72, v0
	v_mov_b32_e32 v73, v0
	v_mov_b32_e32 v74, v0
	v_mov_b32_e32 v75, v0
	v_mov_b32_e32 v76, v0
	v_mov_b32_e32 v77, v0
	v_mov_b32_e32 v78, v0
	v_mov_b32_e32 v79, v0
	v_mov_b32_e32 v88, v0
	v_mov_b32_e32 v89, v0
	v_mov_b32_e32 v90, v0
	v_mov_b32_e32 v91, v0
	v_mov_b32_e32 v92, v0
	v_mov_b32_e32 v93, v0
	v_mov_b32_e32 v94, v0
	v_mov_b32_e32 v95, v0
	v_mov_b32_e32 v104, v0
	v_mov_b32_e32 v105, v0
	v_mov_b32_e32 v106, v0
	v_mov_b32_e32 v107, v0
	v_mov_b32_e32 v108, v0
	v_mov_b32_e32 v109, v0
	v_mov_b32_e32 v110, v0
	v_mov_b32_e32 v111, v0
	v_mov_b32_e32 v120, v0
	v_mov_b32_e32 v121, v0
	v_mov_b32_e32 v122, v0
	v_mov_b32_e32 v123, v0
	v_mov_b32_e32 v124, v0
	v_mov_b32_e32 v125, v0
	v_mov_b32_e32 v126, v0
	v_mov_b32_e32 v127, v0
	.p2align 6

.LBB0_516:
	s_add_u32 s68, s54, s6
	s_addc_u32 s69, s66, s7
	s_and_b64 s[6:7], s[44:45], exec
	v_mov_b32_e32 v0, 0
	s_cselect_b32 s47, s69, s41
	s_cselect_b32 s49, s68, s40
	s_mov_b32 s6, 0
	s_mov_b64 s[84:85], -1
	s_mov_b64 s[86:87], 0
	v_mov_b32_e32 v1, v0
	v_mov_b32_e32 v2, v0
	v_mov_b32_e32 v3, v0
	v_mov_b32_e32 v4, v0
	v_mov_b32_e32 v5, v0
	v_mov_b32_e32 v6, v0
	v_mov_b32_e32 v7, v0
	v_mov_b32_e32 v8, v0
	v_mov_b32_e32 v9, v0
	v_mov_b32_e32 v10, v0
	v_mov_b32_e32 v11, v0
	v_mov_b32_e32 v12, v0
	v_mov_b32_e32 v13, v0
	v_mov_b32_e32 v14, v0
	v_mov_b32_e32 v15, v0
	v_mov_b32_e32 v24, v0
	v_mov_b32_e32 v25, v0
	v_mov_b32_e32 v26, v0
	v_mov_b32_e32 v27, v0
	v_mov_b32_e32 v28, v0
	v_mov_b32_e32 v29, v0
	v_mov_b32_e32 v30, v0
	v_mov_b32_e32 v31, v0
	v_mov_b32_e32 v40, v0
	v_mov_b32_e32 v41, v0
	v_mov_b32_e32 v42, v0
	v_mov_b32_e32 v43, v0
	v_mov_b32_e32 v44, v0
	v_mov_b32_e32 v45, v0
	v_mov_b32_e32 v46, v0
	v_mov_b32_e32 v47, v0
	v_mov_b32_e32 v16, v0
	v_mov_b32_e32 v17, v0
	v_mov_b32_e32 v18, v0
	v_mov_b32_e32 v19, v0
	v_mov_b32_e32 v20, v0
	v_mov_b32_e32 v21, v0
	v_mov_b32_e32 v22, v0
	v_mov_b32_e32 v23, v0
	v_mov_b32_e32 v32, v0
	v_mov_b32_e32 v33, v0
	v_mov_b32_e32 v34, v0
	v_mov_b32_e32 v35, v0
	v_mov_b32_e32 v36, v0
	v_mov_b32_e32 v37, v0
	v_mov_b32_e32 v38, v0
	v_mov_b32_e32 v39, v0
	v_mov_b32_e32 v48, v0
	v_mov_b32_e32 v49, v0
	v_mov_b32_e32 v50, v0
	v_mov_b32_e32 v51, v0
	v_mov_b32_e32 v52, v0
	v_mov_b32_e32 v53, v0
	v_mov_b32_e32 v54, v0
	v_mov_b32_e32 v55, v0
	v_mov_b32_e32 v56, v0
	v_mov_b32_e32 v57, v0
	v_mov_b32_e32 v58, v0
	v_mov_b32_e32 v59, v0
	v_mov_b32_e32 v60, v0
	v_mov_b32_e32 v61, v0
	v_mov_b32_e32 v62, v0
	v_mov_b32_e32 v63, v0
	v_mov_b32_e32 v64, v0
	v_mov_b32_e32 v65, v0
	v_mov_b32_e32 v66, v0
	v_mov_b32_e32 v67, v0
	v_mov_b32_e32 v68, v0
	v_mov_b32_e32 v69, v0
	v_mov_b32_e32 v70, v0
	v_mov_b32_e32 v71, v0
	v_mov_b32_e32 v72, v0
	v_mov_b32_e32 v73, v0
	v_mov_b32_e32 v74, v0
	v_mov_b32_e32 v75, v0
	v_mov_b32_e32 v76, v0
	v_mov_b32_e32 v77, v0
	v_mov_b32_e32 v78, v0
	v_mov_b32_e32 v79, v0
	v_mov_b32_e32 v88, v0
	v_mov_b32_e32 v89, v0
	v_mov_b32_e32 v90, v0
	v_mov_b32_e32 v91, v0
	v_mov_b32_e32 v92, v0
	v_mov_b32_e32 v93, v0
	v_mov_b32_e32 v94, v0
	v_mov_b32_e32 v95, v0
	v_mov_b32_e32 v104, v0
	v_mov_b32_e32 v105, v0
	v_mov_b32_e32 v106, v0
	v_mov_b32_e32 v107, v0
	v_mov_b32_e32 v108, v0
	v_mov_b32_e32 v109, v0
	v_mov_b32_e32 v110, v0
	v_mov_b32_e32 v111, v0
	v_mov_b32_e32 v80, v0
	v_mov_b32_e32 v81, v0
	v_mov_b32_e32 v82, v0
	v_mov_b32_e32 v83, v0
	v_mov_b32_e32 v84, v0
	v_mov_b32_e32 v85, v0
	v_mov_b32_e32 v86, v0
	v_mov_b32_e32 v87, v0
	v_mov_b32_e32 v96, v0
	v_mov_b32_e32 v97, v0
	v_mov_b32_e32 v98, v0
	v_mov_b32_e32 v99, v0
	v_mov_b32_e32 v100, v0
	v_mov_b32_e32 v101, v0
	v_mov_b32_e32 v102, v0
	v_mov_b32_e32 v103, v0
	v_mov_b32_e32 v112, v0
	v_mov_b32_e32 v113, v0
	v_mov_b32_e32 v114, v0
	v_mov_b32_e32 v115, v0
	v_mov_b32_e32 v116, v0
	v_mov_b32_e32 v117, v0
	v_mov_b32_e32 v118, v0
	v_mov_b32_e32 v119, v0
	v_mov_b32_e32 v120, v0
	v_mov_b32_e32 v121, v0
	v_mov_b32_e32 v122, v0
	v_mov_b32_e32 v123, v0
	v_mov_b32_e32 v124, v0
	v_mov_b32_e32 v125, v0
	v_mov_b32_e32 v126, v0
	v_mov_b32_e32 v127, v0
	.p2align 6

.LBB0_544:
	s_ashr_i32 s47, s46, 31
	s_lshl_b64 s[6:7], s[46:47], 9
	s_add_u32 s48, s54, s6
	s_addc_u32 s49, s66, s7
	s_and_b64 s[8:9], s[42:43], exec
	s_cselect_b32 s47, s49, s41
	s_cselect_b32 s89, s48, s40
	s_ashr_i32 s45, s44, 31
	s_lshl_b64 s[8:9], s[44:45], 19
	s_add_u32 s6, s17, s6
	s_addc_u32 s7, s30, s7
	s_add_u32 s50, s6, s8
	s_addc_u32 s51, s7, s9
	s_and_b64 s[6:7], s[42:43], exec
	v_mov_b32_e32 v0, 0
	s_cselect_b32 s45, s51, s39
	s_cselect_b32 s90, s50, s38
	s_mov_b32 s6, 0
	s_mov_b64 s[68:69], -1
	s_mov_b64 s[84:85], 0
	v_mov_b32_e32 v1, v0
	v_mov_b32_e32 v2, v0
	v_mov_b32_e32 v3, v0
	v_mov_b32_e32 v4, v0
	v_mov_b32_e32 v5, v0
	v_mov_b32_e32 v6, v0
	v_mov_b32_e32 v7, v0
	v_mov_b32_e32 v8, v0
	v_mov_b32_e32 v9, v0
	v_mov_b32_e32 v10, v0
	v_mov_b32_e32 v11, v0
	v_mov_b32_e32 v12, v0
	v_mov_b32_e32 v13, v0
	v_mov_b32_e32 v14, v0
	v_mov_b32_e32 v15, v0
	v_mov_b32_e32 v24, v0
	v_mov_b32_e32 v25, v0
	v_mov_b32_e32 v26, v0
	v_mov_b32_e32 v27, v0
	v_mov_b32_e32 v28, v0
	v_mov_b32_e32 v29, v0
	v_mov_b32_e32 v30, v0
	v_mov_b32_e32 v31, v0
	v_mov_b32_e32 v40, v0
	v_mov_b32_e32 v41, v0
	v_mov_b32_e32 v42, v0
	v_mov_b32_e32 v43, v0
	v_mov_b32_e32 v44, v0
	v_mov_b32_e32 v45, v0
	v_mov_b32_e32 v46, v0
	v_mov_b32_e32 v47, v0
	v_mov_b32_e32 v16, v0
	v_mov_b32_e32 v17, v0
	v_mov_b32_e32 v18, v0
	v_mov_b32_e32 v19, v0
	v_mov_b32_e32 v20, v0
	v_mov_b32_e32 v21, v0
	v_mov_b32_e32 v22, v0
	v_mov_b32_e32 v23, v0
	v_mov_b32_e32 v32, v0
	v_mov_b32_e32 v33, v0
	v_mov_b32_e32 v34, v0
	v_mov_b32_e32 v35, v0
	v_mov_b32_e32 v36, v0
	v_mov_b32_e32 v37, v0
	v_mov_b32_e32 v38, v0
	v_mov_b32_e32 v39, v0
	v_mov_b32_e32 v48, v0
	v_mov_b32_e32 v49, v0
	v_mov_b32_e32 v50, v0
	v_mov_b32_e32 v51, v0
	v_mov_b32_e32 v52, v0
	v_mov_b32_e32 v53, v0
	v_mov_b32_e32 v54, v0
	v_mov_b32_e32 v55, v0
	v_mov_b32_e32 v56, v0
	v_mov_b32_e32 v57, v0
	v_mov_b32_e32 v58, v0
	v_mov_b32_e32 v59, v0
	v_mov_b32_e32 v60, v0
	v_mov_b32_e32 v61, v0
	v_mov_b32_e32 v62, v0
	v_mov_b32_e32 v63, v0
	v_mov_b32_e32 v64, v0
	v_mov_b32_e32 v65, v0
	v_mov_b32_e32 v66, v0
	v_mov_b32_e32 v67, v0
	v_mov_b32_e32 v68, v0
	v_mov_b32_e32 v69, v0
	v_mov_b32_e32 v70, v0
	v_mov_b32_e32 v71, v0
	v_mov_b32_e32 v72, v0
	v_mov_b32_e32 v73, v0
	v_mov_b32_e32 v74, v0
	v_mov_b32_e32 v75, v0
	v_mov_b32_e32 v76, v0
	v_mov_b32_e32 v77, v0
	v_mov_b32_e32 v78, v0
	v_mov_b32_e32 v79, v0
	v_mov_b32_e32 v88, v0
	v_mov_b32_e32 v89, v0
	v_mov_b32_e32 v90, v0
	v_mov_b32_e32 v91, v0
	v_mov_b32_e32 v92, v0
	v_mov_b32_e32 v93, v0
	v_mov_b32_e32 v94, v0
	v_mov_b32_e32 v95, v0
	v_mov_b32_e32 v104, v0
	v_mov_b32_e32 v105, v0
	v_mov_b32_e32 v106, v0
	v_mov_b32_e32 v107, v0
	v_mov_b32_e32 v108, v0
	v_mov_b32_e32 v109, v0
	v_mov_b32_e32 v110, v0
	v_mov_b32_e32 v111, v0
	v_mov_b32_e32 v80, v0
	v_mov_b32_e32 v81, v0
	v_mov_b32_e32 v82, v0
	v_mov_b32_e32 v83, v0
	v_mov_b32_e32 v84, v0
	v_mov_b32_e32 v85, v0
	v_mov_b32_e32 v86, v0
	v_mov_b32_e32 v87, v0
	v_mov_b32_e32 v96, v0
	v_mov_b32_e32 v97, v0
	v_mov_b32_e32 v98, v0
	v_mov_b32_e32 v99, v0
	v_mov_b32_e32 v100, v0
	v_mov_b32_e32 v101, v0
	v_mov_b32_e32 v102, v0
	v_mov_b32_e32 v103, v0
	v_mov_b32_e32 v112, v0
	v_mov_b32_e32 v113, v0
	v_mov_b32_e32 v114, v0
	v_mov_b32_e32 v115, v0
	v_mov_b32_e32 v116, v0
	v_mov_b32_e32 v117, v0
	v_mov_b32_e32 v118, v0
	v_mov_b32_e32 v119, v0
	v_mov_b32_e32 v120, v0
	v_mov_b32_e32 v121, v0
	v_mov_b32_e32 v122, v0
	v_mov_b32_e32 v123, v0
	v_mov_b32_e32 v124, v0
	v_mov_b32_e32 v125, v0
	v_mov_b32_e32 v126, v0
	v_mov_b32_e32 v127, v0
	.p2align 6

.LBB0_617:
	v_lshl_add_u64 v[142:143], s[40:41], 0, v[110:111]
	v_lshl_add_u64 v[156:157], s[40:41], 0, v[128:129]
	v_lshl_add_u64 v[158:159], s[4:5], 0, v[130:131]
	v_lshl_add_u64 v[160:161], s[4:5], 0, v[140:141]
	s_mov_b32 s3, -2
	s_mov_b64 s[46:47], 0
	.p2align 6

.LBB0_740:
	s_ashr_i32 s13, s12, 31
	s_lshl_b64 s[6:7], s[12:13], 19
	s_add_u32 s44, s60, s6
	s_addc_u32 s45, s61, s7
	s_and_b64 s[6:7], s[40:41], exec
	s_cselect_b32 s5, s45, s3
	s_cselect_b32 s11, s44, s2
	s_add_u32 s13, s46, 0x100
	s_addc_u32 s14, s47, 0
	s_add_u32 s6, s2, 0x40080
	s_addc_u32 s7, s3, 0
	v_lshl_add_u64 v[138:139], s[6:7], 0, v[134:135]
	v_lshl_add_u64 v[140:141], s[6:7], 0, v[136:137]
	s_mov_b32 s15, -2
	s_mov_b64 s[40:41], 0
	.p2align 6

.LBB0_875:
	v_lshl_add_u64 v[142:143], s[42:43], 0, v[110:111]
	v_lshl_add_u64 v[156:157], s[42:43], 0, v[128:129]
	v_lshl_add_u64 v[158:159], s[12:13], 0, v[130:131]
	v_lshl_add_u64 v[160:161], s[12:13], 0, v[140:141]
	s_mov_b32 s3, -2
	s_mov_b64 s[48:49], 0
	.p2align 6

.LBB0_992:
	s_ashr_i32 s43, s42, 31
	s_lshl_b64 s[8:9], s[42:43], 19
	s_add_u32 s44, s60, s8
	s_addc_u32 s45, s61, s9
	s_and_b64 s[8:9], s[36:37], exec
	s_cselect_b32 s14, s45, s7
	s_cselect_b32 s15, s44, s6
	s_ashr_i32 s41, s40, 31
	s_lshl_b64 s[8:9], s[40:41], 19
	s_add_u32 s46, s24, s8
	s_addc_u32 s47, s25, s9
	s_and_b64 s[8:9], s[36:37], exec
	s_cselect_b32 s16, s47, s51
	s_cselect_b32 s17, s46, s50
	s_add_u32 s48, s6, 0x40080
	s_addc_u32 s49, s7, 0
	s_add_u32 s23, s50, 0x100
	v_mov_b32_e32 v0, 0
	s_addc_u32 s30, s51, 0
	s_mov_b32 s31, -2
	v_mov_b32_e32 v1, v0
	v_mov_b32_e32 v2, v0
	v_mov_b32_e32 v3, v0
	v_mov_b32_e32 v4, v0
	v_mov_b32_e32 v5, v0
	v_mov_b32_e32 v6, v0
	v_mov_b32_e32 v7, v0
	v_mov_b32_e32 v16, v0
	v_mov_b32_e32 v17, v0
	v_mov_b32_e32 v18, v0
	v_mov_b32_e32 v19, v0
	v_mov_b32_e32 v20, v0
	v_mov_b32_e32 v21, v0
	v_mov_b32_e32 v22, v0
	v_mov_b32_e32 v23, v0
	v_mov_b32_e32 v32, v0
	v_mov_b32_e32 v33, v0
	v_mov_b32_e32 v34, v0
	v_mov_b32_e32 v35, v0
	v_mov_b32_e32 v36, v0
	v_mov_b32_e32 v37, v0
	v_mov_b32_e32 v38, v0
	v_mov_b32_e32 v39, v0
	v_mov_b32_e32 v48, v0
	v_mov_b32_e32 v49, v0
	v_mov_b32_e32 v50, v0
	v_mov_b32_e32 v51, v0
	v_mov_b32_e32 v52, v0
	v_mov_b32_e32 v53, v0
	v_mov_b32_e32 v54, v0
	v_mov_b32_e32 v55, v0
	v_mov_b32_e32 v8, v0
	v_mov_b32_e32 v9, v0
	v_mov_b32_e32 v10, v0
	v_mov_b32_e32 v11, v0
	v_mov_b32_e32 v12, v0
	v_mov_b32_e32 v13, v0
	v_mov_b32_e32 v14, v0
	v_mov_b32_e32 v15, v0
	v_mov_b32_e32 v24, v0
	v_mov_b32_e32 v25, v0
	v_mov_b32_e32 v26, v0
	v_mov_b32_e32 v27, v0
	v_mov_b32_e32 v28, v0
	v_mov_b32_e32 v29, v0
	v_mov_b32_e32 v30, v0
	v_mov_b32_e32 v31, v0
	v_mov_b32_e32 v40, v0
	v_mov_b32_e32 v41, v0
	v_mov_b32_e32 v42, v0
	v_mov_b32_e32 v43, v0
	v_mov_b32_e32 v44, v0
	v_mov_b32_e32 v45, v0
	v_mov_b32_e32 v46, v0
	v_mov_b32_e32 v47, v0
	v_mov_b32_e32 v56, v0
	v_mov_b32_e32 v57, v0
	v_mov_b32_e32 v58, v0
	v_mov_b32_e32 v59, v0
	v_mov_b32_e32 v60, v0
	v_mov_b32_e32 v61, v0
	v_mov_b32_e32 v62, v0
	v_mov_b32_e32 v63, v0
	v_mov_b32_e32 v64, v0
	v_mov_b32_e32 v65, v0
	v_mov_b32_e32 v66, v0
	v_mov_b32_e32 v67, v0
	v_mov_b32_e32 v68, v0
	v_mov_b32_e32 v69, v0
	v_mov_b32_e32 v70, v0
	v_mov_b32_e32 v71, v0
	v_mov_b32_e32 v80, v0
	v_mov_b32_e32 v81, v0
	v_mov_b32_e32 v82, v0
	v_mov_b32_e32 v83, v0
	v_mov_b32_e32 v84, v0
	v_mov_b32_e32 v85, v0
	v_mov_b32_e32 v86, v0
	v_mov_b32_e32 v87, v0
	v_mov_b32_e32 v96, v0
	v_mov_b32_e32 v97, v0
	v_mov_b32_e32 v98, v0
	v_mov_b32_e32 v99, v0
	v_mov_b32_e32 v100, v0
	v_mov_b32_e32 v101, v0
	v_mov_b32_e32 v102, v0
	v_mov_b32_e32 v103, v0
	v_mov_b32_e32 v112, v0
	v_mov_b32_e32 v113, v0
	v_mov_b32_e32 v114, v0
	v_mov_b32_e32 v115, v0
	v_mov_b32_e32 v116, v0
	v_mov_b32_e32 v117, v0
	v_mov_b32_e32 v118, v0
	v_mov_b32_e32 v119, v0
	v_mov_b32_e32 v72, v0
	v_mov_b32_e32 v73, v0
	v_mov_b32_e32 v74, v0
	v_mov_b32_e32 v75, v0
	v_mov_b32_e32 v76, v0
	v_mov_b32_e32 v77, v0
	v_mov_b32_e32 v78, v0
	v_mov_b32_e32 v79, v0
	v_mov_b32_e32 v88, v0
	v_mov_b32_e32 v89, v0
	v_mov_b32_e32 v90, v0
	v_mov_b32_e32 v91, v0
	v_mov_b32_e32 v92, v0
	v_mov_b32_e32 v93, v0
	v_mov_b32_e32 v94, v0
	v_mov_b32_e32 v95, v0
	v_mov_b32_e32 v104, v0
	v_mov_b32_e32 v105, v0
	v_mov_b32_e32 v106, v0
	v_mov_b32_e32 v107, v0
	v_mov_b32_e32 v108, v0
	v_mov_b32_e32 v109, v0
	v_mov_b32_e32 v110, v0
	v_mov_b32_e32 v111, v0
	v_mov_b32_e32 v120, v0
	v_mov_b32_e32 v121, v0
	v_mov_b32_e32 v122, v0
	v_mov_b32_e32 v123, v0
	v_mov_b32_e32 v124, v0
	v_mov_b32_e32 v125, v0
	v_mov_b32_e32 v126, v0
	v_mov_b32_e32 v127, v0
	.p2align 6

.LBB0_1017:
	s_ashr_i32 s43, s42, 31
	s_lshl_b64 s[8:9], s[42:43], 19
	v_readlane_b32 s18, v252, 41
	s_add_u32 s44, s18, s8
	v_readlane_b32 s8, v252, 42
	s_addc_u32 s45, s8, s9
	s_and_b64 s[8:9], s[38:39], exec
	s_cselect_b32 s31, s45, s49
	s_cselect_b32 s33, s44, s48
	s_ashr_i32 s41, s40, 31
	s_lshl_b64 s[8:9], s[40:41], 19
	v_readlane_b32 s18, v251, 41
	v_readlane_b32 s19, v251, 42
	s_add_u32 s46, s18, s8
	s_addc_u32 s47, s19, s9
	s_and_b64 s[8:9], s[38:39], exec
	s_cselect_b32 s37, s47, s51
	s_cselect_b32 s41, s46, s50
	s_add_u32 s48, s48, 0x40080
	s_addc_u32 s49, s49, 0
	s_add_u32 s43, s50, 0x100
	v_mov_b32_e32 v0, 0
	s_addc_u32 s50, s51, 0
	s_mov_b32 s51, -2
	v_mov_b32_e32 v1, v0
	v_mov_b32_e32 v2, v0
	v_mov_b32_e32 v3, v0
	v_mov_b32_e32 v4, v0
	v_mov_b32_e32 v5, v0
	v_mov_b32_e32 v6, v0
	v_mov_b32_e32 v7, v0
	v_mov_b32_e32 v8, v0
	v_mov_b32_e32 v9, v0
	v_mov_b32_e32 v10, v0
	v_mov_b32_e32 v11, v0
	v_mov_b32_e32 v12, v0
	v_mov_b32_e32 v13, v0
	v_mov_b32_e32 v14, v0
	v_mov_b32_e32 v15, v0
	v_mov_b32_e32 v24, v0
	v_mov_b32_e32 v25, v0
	v_mov_b32_e32 v26, v0
	v_mov_b32_e32 v27, v0
	v_mov_b32_e32 v28, v0
	v_mov_b32_e32 v29, v0
	v_mov_b32_e32 v30, v0
	v_mov_b32_e32 v31, v0
	v_mov_b32_e32 v40, v0
	v_mov_b32_e32 v41, v0
	v_mov_b32_e32 v42, v0
	v_mov_b32_e32 v43, v0
	v_mov_b32_e32 v44, v0
	v_mov_b32_e32 v45, v0
	v_mov_b32_e32 v46, v0
	v_mov_b32_e32 v47, v0
	v_mov_b32_e32 v16, v0
	v_mov_b32_e32 v17, v0
	v_mov_b32_e32 v18, v0
	v_mov_b32_e32 v19, v0
	v_mov_b32_e32 v20, v0
	v_mov_b32_e32 v21, v0
	v_mov_b32_e32 v22, v0
	v_mov_b32_e32 v23, v0
	v_mov_b32_e32 v32, v0
	v_mov_b32_e32 v33, v0
	v_mov_b32_e32 v34, v0
	v_mov_b32_e32 v35, v0
	v_mov_b32_e32 v36, v0
	v_mov_b32_e32 v37, v0
	v_mov_b32_e32 v38, v0
	v_mov_b32_e32 v39, v0
	v_mov_b32_e32 v48, v0
	v_mov_b32_e32 v49, v0
	v_mov_b32_e32 v50, v0
	v_mov_b32_e32 v51, v0
	v_mov_b32_e32 v52, v0
	v_mov_b32_e32 v53, v0
	v_mov_b32_e32 v54, v0
	v_mov_b32_e32 v55, v0
	v_mov_b32_e32 v56, v0
	v_mov_b32_e32 v57, v0
	v_mov_b32_e32 v58, v0
	v_mov_b32_e32 v59, v0
	v_mov_b32_e32 v60, v0
	v_mov_b32_e32 v61, v0
	v_mov_b32_e32 v62, v0
	v_mov_b32_e32 v63, v0
	v_mov_b32_e32 v64, v0
	v_mov_b32_e32 v65, v0
	v_mov_b32_e32 v66, v0
	v_mov_b32_e32 v67, v0
	v_mov_b32_e32 v68, v0
	v_mov_b32_e32 v69, v0
	v_mov_b32_e32 v70, v0
	v_mov_b32_e32 v71, v0
	v_mov_b32_e32 v72, v0
	v_mov_b32_e32 v73, v0
	v_mov_b32_e32 v74, v0
	v_mov_b32_e32 v75, v0
	v_mov_b32_e32 v76, v0
	v_mov_b32_e32 v77, v0
	v_mov_b32_e32 v78, v0
	v_mov_b32_e32 v79, v0
	v_mov_b32_e32 v88, v0
	v_mov_b32_e32 v89, v0
	v_mov_b32_e32 v90, v0
	v_mov_b32_e32 v91, v0
	v_mov_b32_e32 v92, v0
	v_mov_b32_e32 v93, v0
	v_mov_b32_e32 v94, v0
	v_mov_b32_e32 v95, v0
	v_mov_b32_e32 v104, v0
	v_mov_b32_e32 v105, v0
	v_mov_b32_e32 v106, v0
	v_mov_b32_e32 v107, v0
	v_mov_b32_e32 v108, v0
	v_mov_b32_e32 v109, v0
	v_mov_b32_e32 v110, v0
	v_mov_b32_e32 v111, v0
	v_mov_b32_e32 v80, v0
	v_mov_b32_e32 v81, v0
	v_mov_b32_e32 v82, v0
	v_mov_b32_e32 v83, v0
	v_mov_b32_e32 v84, v0
	v_mov_b32_e32 v85, v0
	v_mov_b32_e32 v86, v0
	v_mov_b32_e32 v87, v0
	v_mov_b32_e32 v96, v0
	v_mov_b32_e32 v97, v0
	v_mov_b32_e32 v98, v0
	v_mov_b32_e32 v99, v0
	v_mov_b32_e32 v100, v0
	v_mov_b32_e32 v101, v0
	v_mov_b32_e32 v102, v0
	v_mov_b32_e32 v103, v0
	v_mov_b32_e32 v112, v0
	v_mov_b32_e32 v113, v0
	v_mov_b32_e32 v114, v0
	v_mov_b32_e32 v115, v0
	v_mov_b32_e32 v116, v0
	v_mov_b32_e32 v117, v0
	v_mov_b32_e32 v118, v0
	v_mov_b32_e32 v119, v0
	v_mov_b32_e32 v120, v0
	v_mov_b32_e32 v121, v0
	v_mov_b32_e32 v122, v0
	v_mov_b32_e32 v123, v0
	v_mov_b32_e32 v124, v0
	v_mov_b32_e32 v125, v0
	v_mov_b32_e32 v126, v0
	v_mov_b32_e32 v127, v0
	.p2align 6

.LBB0_1192:
	v_lshl_add_u64 v[142:143], s[46:47], 0, v[110:111]
	v_lshl_add_u64 v[156:157], s[46:47], 0, v[128:129]
	v_lshl_add_u64 v[158:159], s[42:43], 0, v[130:131]
	v_lshl_add_u64 v[160:161], s[42:43], 0, v[140:141]
	s_mov_b32 s11, -2
	s_mov_b64 s[50:51], 0
	.p2align 6

.LBB0_1237:
	s_add_u32 s48, s46, 0x100
	s_addc_u32 s49, s47, 0
	s_add_u32 s8, s42, 0xc0080
	s_addc_u32 s9, s43, 0
	v_lshl_add_u64 v[138:139], s[8:9], 0, v[134:135]
	v_lshl_add_u64 v[140:141], s[8:9], 0, v[136:137]
	s_mov_b32 s50, -2
	s_mov_b64 s[46:47], 0
	.p2align 6
